# de-synchronise HBM store bursts: input-projection GEMM phase entered (blk&3) x 2.1us apart so the four XCD groups' EpiWin store bursts overlap the other groups' K-loops
# baseline (speedup 1.0000x reference)
; #define PG8_STAGE(bufoff, gbase, voff) do { _Pragma("unroll") for (int _i = 0; _i < 2; ++_i) \
;         __builtin_amdgcn_global_load_lds((const unsigned*)((const char*)(gbase) + (voff)[_i]), (PG8_LAS unsigned*)(lds + (bufoff) + ldsw + _i * 8192), 16, 0, 0); } while (0)
; #define PG8_WAIT_V(n) asm volatile("s_waitcnt vmcnt(" #n ")" ::: "memory")
; #define PG8_BAR __builtin_amdgcn_s_barrier()
;     ...
;     if constexpr (SP2) {
;         PG8_STAGE(PG8_SB(0, 0), cB, voffB); PG8_STAGE(PG8_SB(0, 1), cB + hstepB, voffB); PG8_STAGE(PG8_SA(0, 0), cA, voffA); PG8_STAGE(PG8_SA(0, 1), cA + hstep, voffA);
;         if (wr == 1) PG8_BAR;
;         PG8_WAIT_V(2); PG8_BAR;
;         PG8_STAGE(PG8_SB(1, 0), cB + kstepB, voffB); PG8_STAGE(PG8_SA(1, 0), cA + kstep, voffA); PG8_STAGE(PG8_SB(1, 1), cB + hstepB + kstepB, voffB);
;         PG8_WAIT_V(6); PG8_BAR;
.LBB0_363:
	s_add_u32 s22, s46, 0x300000
	s_addc_u32 s23, s47, 0
	s_add_u32 s24, s46, 0x400000
	s_addc_u32 s25, s47, 0
	s_add_u32 s57, s46, 0x33800000
	s_addc_u32 s58, s47, 0
	s_add_u32 s59, s46, 0x700000
	s_addc_u32 s60, s47, 0
	s_and_b32 s61, s6, 3
	s_lshl_b32 s62, s52, 6
	s_lshl_b32 s5, s52, 13
	s_lshl_b32 s7, s6, 5
	s_lshl_b32 s26, s61, 12
	s_add_u32 s10, s0, 0x8000
	v_mov_b32_e32 v143, v163
	s_addc_u32 s11, s1, 0
	v_mov_b32_e32 v147, v163
	s_add_i32 m0, s21, 0x18000
	v_lshl_add_u64 v[12:13], s[10:11], 0, v[142:143]
	s_waitcnt vmcnt(2)
	s_barrier
	global_load_lds_dwordx4 v[12:13], off
	v_lshl_add_u64 v[12:13], s[10:11], 0, v[146:147]
	s_add_i32 m0, s21, 0x1a000
	s_add_i32 s63, s21, 0x8000
	s_add_i32 s64, s21, 0xa000
	global_load_lds_dwordx4 v[12:13], off
	v_lshl_add_u64 v[2:3], v[2:3], 0, s[78:79]
	s_mov_b32 m0, s63
	s_add_u32 s10, s0, 0xc000
	global_load_lds_dwordx4 v[2:3], off
	v_lshl_add_u64 v[2:3], v[4:5], 0, s[78:79]
	s_mov_b32 m0, s64
	s_addc_u32 s11, s1, 0
	global_load_lds_dwordx4 v[2:3], off
	s_add_i32 m0, s21, 0x1c000
	v_lshl_add_u64 v[2:3], s[10:11], 0, v[142:143]
	global_load_lds_dwordx4 v[2:3], off
	v_lshl_add_u64 v[2:3], s[10:11], 0, v[146:147]
	s_add_i32 m0, s21, 0x1e000
	v_bfe_u32 v160, v1, 4, 2
	global_load_lds_dwordx4 v[2:3], off
	v_and_b32_e32 v159, 15, v1
	v_lshlrev_b32_e32 v2, 4, v160
	v_lshlrev_b32_e32 v3, 2, v1
	v_lshl_or_b32 v2, v159, 6, v2
	v_and_b32_e32 v3, 32, v3
	v_bitop3_b32 v4, v2, s5, v3 bitop3:0xde
	v_bitop3_b32 v161, s26, v2, v3 bitop3:0xf6
	s_or_b32 s65, s61, 8
	v_and_b32_e32 v2, 1, v1
	s_cmpk_lt_u32 s4, 0x100
	v_cmp_eq_u32_e64 s[4:5], 0, v2
	v_lshlrev_b32_e32 v2, 6, v2
	v_mov_b32_e32 v3, v163
	v_lshl_add_u64 v[148:149], s[16:17], 0, v[2:3]
	v_lshlrev_b32_e32 v2, 15, v6
	s_cselect_b64 s[26:27], -1, 0
	s_bfe_u32 s67, s6, 0x10001
	s_and_b32 s68, s7, 32
	s_ashr_i32 s69, s45, 31
	s_ashr_i32 s70, s44, 31
	s_lshl_b32 s6, s61, 6
	v_and_b32_e32 v2, 0xffff0000, v2
	s_add_u32 s71, s57, s6
	v_lshl_add_u32 v2, v7, 12, v2
	v_and_b32_e32 v3, 1, v6
	s_addc_u32 s72, s58, 0
	v_lshl_or_b32 v2, v3, 6, v2
	s_add_u32 s6, s46, s6
	v_lshl_add_u32 v150, v8, 1, v2
	v_lshlrev_b32_e32 v2, 15, v9
	s_addc_u32 s7, s47, 0
	v_and_b32_e32 v2, 0xffff0000, v2
	s_waitcnt vmcnt(6)
	s_add_u32 s73, s6, 0x2d800000
	v_lshl_add_u32 v2, v10, 12, v2
	v_and_b32_e32 v3, 1, v9
	v_ashrrev_i32_e32 v173, 1, v1
	s_addc_u32 s74, s7, 0
	s_add_i32 s6, 0, 0x20400
	v_lshl_or_b32 v2, v3, 6, v2
	s_mov_b32 s66, 0
	v_lshl_add_u32 v174, v173, 2, s6
	v_mov_b32_e32 v151, v163
	v_lshl_add_u32 v152, v11, 1, v2
	v_mov_b32_e32 v153, v163
	s_mov_b32 s75, -1
	v_add_u32_e32 v175, 0, v4
	s_barrier
	s_and_b32 s96, s44, 3
	s_cmp_eq_u32 s96, 0
	s_cbranch_scc1 .Lwin_stg_done
.Lwin_stg_loop:
	s_sleep 72
	s_sub_u32 s96, s96, 1
	s_cmp_lg_u32 s96, 0
	s_cbranch_scc1 .Lwin_stg_loop
.Lwin_stg_done:
	s_branch .LBB0_366
.LBB0_364:
	s_mov_b64 s[0:1], 0
